# saddr K-loops + GEMM prologues issue the second LDS-DMA batch before waiting on the first (run 1)
# baseline (speedup 1.0000x reference)
;     __device__ bool next(int i, Unit& u) const { if (r0 + i >= r1) return false; return base.next(r0 + i, u); }
;     __device__ bool next(int i, Unit& u) const { const int L = i * G + c; if (L >= 256) return false; u.pm = L; u.pn = L >> 3; return true; }
; #define PG8_WAIT_V(n) asm volatile("s_waitcnt vmcnt(" #n ")" ::: "memory")
; #define PG8_BAR __builtin_amdgcn_s_barrier()
; #define lane lane_id()
; template <class Epi, class Sched>
; __device__ __forceinline__ void gemm_phase(LAS unsigned char* lds, const Gemm g, const Sched& S, const Epi& E, int wave_id) {
;     ...
;     const int wid = wave_id, lane = tid & 63, wr = wid >> 2, wc = wid & 3, fr = lane & 15, fq = lane >> 4;
;     const int K = g.K, nt = K / BK;
;     unsigned voffA[2], voffB[2];
; #pragma unroll
;     for (int i = 0; i < 2; ++i) { int R, C; stage_rc(tid * 16 + i * 8192, R, C); const int Rb = (R & ~31) + perm32(R & 31);
;         voffA[i] = (unsigned)(R * g.lda + C) * 2u; voffB[i] = (unsigned)(Rb * g.ldb + C) * 2u; }
;     const size_t kstep = (size_t)(BK * 2);
;     const size_t hstepA = (size_t)HALF * g.lda * 2, hstepB = (size_t)HALF * g.ldb * 2;
;     const size_t tstepA = 2 * hstepA, tstepB = 2 * hstepB;
;     const unsigned ldsw = (unsigned)wid * 1024u;
;     const int aoff = lds_byte(wr * 64 + fr, fq * 8), boff = lds_byte(wc * 32 + fr, fq * 8);
;     ...
;     Unit cur, nxt; int ui = 0;
;     if (!S.next(0, cur)) return;
;     f32x4 acc[2][2][4][2];
; #pragma unroll
;     for (int a = 0; a < 2; ++a)
; #pragma unroll
;         for (int b = 0; b < 2; ++b)
; #pragma unroll
;             for (int m = 0; m < 4; ++m)
; #pragma unroll
;                 for (int n = 0; n < 2; ++n) acc[a][b][m][n] = (f32x4){0.f, 0.f, 0.f, 0.f};
;     bf16x8 At[4][2], B0[2][2], B1[2][2];
;     const char* cA = (const char*)g.A + (size_t)cur.pm * tstepA; const char* cB = (const char*)g.Bt + (size_t)cur.pn * tstepB;
;     PG8_STAGE(PG8_SB(0, 0), cB, voffB); PG8_STAGE(PG8_SB(0, 1), cB + hstepB, voffB); PG8_STAGE(PG8_SA(0, 0), cA, voffA); PG8_STAGE(PG8_SA(0, 1), cA + hstepA, voffA);
;     if (wr == 1) PG8_BAR;
;     PG8_WAIT_V(2); PG8_BAR;
;     PG8_STAGE(PG8_SB(1, 0), cB + kstep, voffB); PG8_STAGE(PG8_SA(1, 0), cA + kstep, voffA); PG8_STAGE(PG8_SB(1, 1), cB + hstepB + kstep, voffB);
;     PG8_WAIT_V(6); PG8_BAR;
.LBB0_246:
	s_lshl_b32 s4, s97, 5
	s_mov_b64 s[22:23], 0x80
	s_and_b32 s7, s4, 0x60
	s_add_i32 m0, s55, 0x18000
	v_lshl_add_u64 v[6:7], v[6:7], 0, s[22:23]
	s_lshl_b32 s61, s2, 6
	s_lshl_b32 s2, s2, 13
	s_lshl_b32 s9, s7, 7
	global_load_lds_dwordx4 v[6:7], off
	v_lshl_add_u64 v[4:5], v[4:5], 0, s[22:23]
	s_add_i32 m0, s55, 0x1a000
	s_add_i32 s62, s55, 0x8000
	s_add_i32 s63, s55, 0xa000
	global_load_lds_dwordx4 v[4:5], off
	v_lshl_add_u64 v[0:1], v[0:1], 0, s[22:23]
	s_mov_b32 m0, s62
	s_add_u32 s4, s12, 0x40080
	global_load_lds_dwordx4 v[0:1], off
	v_lshl_add_u64 v[0:1], v[2:3], 0, s[22:23]
	s_mov_b32 m0, s63
	s_addc_u32 s5, s13, 0
	global_load_lds_dwordx4 v[0:1], off
	s_add_i32 m0, s55, 0x1c000
	s_nop 0
	global_load_lds_dwordx4 v146, s[4:5]
	v_lshl_add_u64 v[0:1], s[4:5], 0, v[150:151]
	s_add_i32 m0, s55, 0x1e000
	v_and_b32_e32 v167, 15, v8
	global_load_lds_dwordx4 v[0:1], off
	s_waitcnt vmcnt(8)
	s_barrier
	v_lshrrev_b32_e32 v0, 1, v8
	v_and_b32_e32 v2, 24, v0
	v_lshlrev_b32_e32 v0, 1, v2
	v_lshlrev_b32_e32 v1, 2, v8
	v_lshl_or_b32 v0, v167, 6, v0
	v_and_b32_e32 v1, 32, v1
	s_cmpk_lt_u32 s80, 0x100
	v_bitop3_b32 v3, v0, s2, v1 bitop3:0xde
	s_cselect_b64 s[24:25], -1, 0
	s_lshl_b32 s2, s7, 2
	s_add_u32 s4, s92, s2
	s_addc_u32 s5, s93, 0
	v_lshlrev_b32_e32 v152, 2, v2
	v_bitop3_b32 v171, v0, s9, v1 bitop3:0xde
	v_lshl_add_u64 v[0:1], s[4:5], 0, v[152:153]
	s_mov_b64 s[4:5], 0x1f4c0000
	v_lshlrev_b32_e32 v152, 5, v167
	v_lshl_add_u64 v[154:155], v[0:1], 0, s[4:5]
	s_add_u32 s26, s92, 0x1f400000
	v_lshl_add_u64 v[0:1], s[92:93], 0, v[152:153]
	v_and_b32_e32 v152, 16, v8
	s_addc_u32 s27, s93, 0
	v_lshl_add_u64 v[0:1], v[0:1], 0, v[152:153]
	s_mov_b64 s[4:5], 0x17400000
	s_add_u32 s28, s92, 0x1a400000
	v_lshl_add_u64 v[156:157], v[0:1], 0, s[4:5]
	v_lshlrev_b32_e32 v0, 14, v9
	s_addc_u32 s29, s93, 0
	v_and_b32_e32 v0, 0xffff8000, v0
	s_add_u32 s30, s92, 0xf400000
	v_lshl_add_u32 v0, v10, 11, v0
	v_and_b32_e32 v1, 1, v9
	s_addc_u32 s31, s93, 0
	v_lshl_or_b32 v0, v1, 6, v0
	s_add_u32 s34, s92, 0x13400000
	v_lshl_add_u32 v158, v11, 1, v0
	v_lshlrev_b32_e32 v0, 14, v12
	s_addc_u32 s35, s93, 0
	v_and_b32_e32 v0, 0xffff8000, v0
	s_waitcnt vmcnt(6)
	s_add_u32 s36, s92, 0x7400000
	v_lshl_add_u32 v0, v13, 11, v0
	v_and_b32_e32 v1, 1, v12
	v_or_b32_e32 v173, s7, v2
	s_addc_u32 s37, s93, 0
	v_readlane_b32 s4, v255, 1
	v_lshl_or_b32 v0, v1, 6, v0
	s_add_i32 s67, 0, 0x10000
	s_add_i32 s72, 0, 0x14000
	v_or_b32_e32 v175, 0xffffee00, v173
	v_or_b32_e32 v177, 0xfffff000, v173
	v_or_b32_e32 v179, 0xffffee80, v173
	v_or_b32_e32 v181, 0xfffff080, v173
	s_ashr_i32 s64, s4, 31
	s_mov_b32 s65, s4
	s_ashr_i32 s66, s66, 31
	v_mov_b32_e32 v159, v153
	v_lshl_add_u32 v160, v14, 1, v0
	v_mov_b32_e32 v161, v153
	v_mov_b64_e32 v[162:163], 0xa00
	v_mov_b64_e32 v[164:165], 0x9ff
	v_add_u32_e32 v183, s67, v171
	v_add_u32_e32 v190, s72, v171
	v_add_u32_e32 v191, 0, v3
	s_movk_i32 s73, 0x300
	s_mov_b32 s74, 0x800000
	s_mov_b32 s75, 0x3f317217
	s_mov_b32 s76, 0x7f800000
	v_mov_b32_e32 v192, 0x41b17218
	s_mov_b32 s77, 0
	s_barrier
	v_readlane_b32 s5, v255, 2
	s_branch .LBB0_249

; #define PG8_STAGE(bufoff, gbase, voff) do { _Pragma("unroll") for (int _i = 0; _i < 2; ++_i) \
;         __builtin_amdgcn_global_load_lds((const unsigned*)((const char*)(gbase) + (voff)[_i]), (LAS unsigned*)(lds + (bufoff) + ldsw + _i * 8192), 16, 0, 0); } while (0)
; #define PG8_WAIT_V(n) asm volatile("s_waitcnt vmcnt(" #n ")" ::: "memory")
; #define PG8_BAR __builtin_amdgcn_s_barrier()
; template <class Epi, class Sched>
; __device__ __forceinline__ void gemm_phase(LAS unsigned char* lds, const Gemm g, const Sched& S, const Epi& E, int wave_id) {
;     ...
;     PG8_STAGE(PG8_SB(0, 0), cB, voffB); PG8_STAGE(PG8_SB(0, 1), cB + hstepB, voffB); PG8_STAGE(PG8_SA(0, 0), cA, voffA); PG8_STAGE(PG8_SA(0, 1), cA + hstepA, voffA);
;     if (wr == 1) PG8_BAR;
;     PG8_WAIT_V(2); PG8_BAR;
;     PG8_STAGE(PG8_SB(1, 0), cB + kstep, voffB); PG8_STAGE(PG8_SA(1, 0), cA + kstep, voffA); PG8_STAGE(PG8_SB(1, 1), cB + hstepB + kstep, voffB);
;     PG8_WAIT_V(6); PG8_BAR;
.LBB0_662:
	s_lshl_b32 s6, s97, 5
	s_and_b32 s14, s6, 0x60
	s_mov_b64 s[6:7], 0x80
	v_readlane_b32 s16, v255, 1
	s_add_i32 m0, s31, 0x18000
	v_lshl_add_u64 v[6:7], v[6:7], 0, s[6:7]
	s_lshl_b32 s12, s9, 13
	s_lshl_b32 s13, s14, 7
	s_ashr_i32 s51, s16, 31
	global_load_lds_dwordx4 v[6:7], off
	v_lshl_add_u64 v[4:5], v[4:5], 0, s[6:7]
	s_add_i32 m0, s31, 0x1a000
	s_add_i32 s52, s31, 0x8000
	s_add_i32 s53, s31, 0xa000
	global_load_lds_dwordx4 v[4:5], off
	v_lshl_add_u64 v[0:1], v[0:1], 0, s[6:7]
	s_mov_b32 m0, s52
	s_add_u32 s10, s36, 0x40080
	global_load_lds_dwordx4 v[0:1], off
	v_lshl_add_u64 v[0:1], v[2:3], 0, s[6:7]
	s_mov_b32 m0, s53
	s_addc_u32 s11, s37, 0
	global_load_lds_dwordx4 v[0:1], off
	s_add_i32 m0, s31, 0x1c000
	s_nop 0
	global_load_lds_dwordx4 v130, s[10:11]
	v_lshl_add_u64 v[0:1], s[10:11], 0, v[134:135]
	s_add_i32 m0, s31, 0x1e000
	s_cmpk_lt_u32 s80, 0x100
	global_load_lds_dwordx4 v[0:1], off
	s_waitcnt vmcnt(8)
	s_barrier
	v_lshrrev_b32_e32 v1, 1, v8
	v_and_b32_e32 v1, 24, v1
	v_and_b32_e32 v0, 15, v8
	v_lshlrev_b32_e32 v2, 1, v1
	v_lshl_or_b32 v158, s9, 6, v0
	v_lshl_or_b32 v0, v0, 6, v2
	v_lshlrev_b32_e32 v2, 2, v8
	v_and_b32_e32 v2, 32, v2
	v_bitop3_b32 v3, v0, s12, v2 bitop3:0xde
	v_bitop3_b32 v159, v0, s13, v2 bitop3:0xde
	v_lshlrev_b32_e32 v0, 14, v9
	v_and_b32_e32 v0, 0xffff8000, v0
	v_or_b32_e32 v160, s14, v1
	v_lshl_add_u32 v0, v10, 11, v0
	v_and_b32_e32 v1, 1, v9
	v_lshl_or_b32 v0, v1, 6, v0
	s_sext_i32_i8 s60, s8
	s_cselect_b64 s[8:9], -1, 0
	s_add_u32 s10, s92, 0x1f400000
	v_lshl_add_u32 v136, v11, 1, v0
	v_lshlrev_b32_e32 v0, 14, v12
	s_addc_u32 s11, s93, 0
	v_and_b32_e32 v0, 0xffff8000, v0
	s_waitcnt vmcnt(6)
	s_add_u32 s12, s92, 0xb400000
	v_lshl_add_u32 v0, v13, 11, v0
	v_and_b32_e32 v1, 1, v12
	s_addc_u32 s13, s93, 0
	v_lshl_or_b32 v0, v1, 6, v0
	s_add_i32 s55, 0, 0x10000
	s_add_i32 s58, 0, 0x14000
	s_mov_b32 s54, s16
	v_mov_b32_e32 v137, v131
	v_lshl_add_u32 v138, v14, 1, v0
	v_mov_b32_e32 v139, v131
	v_add_u32_e32 v161, s55, v159
	v_add_u32_e32 v162, s58, v159
	v_add_u32_e32 v163, 0, v3
	s_mov_b32 s14, 0x437f0000
	s_mov_b32 s59, 0xb400000
	v_mov_b64_e32 v[140:141], 0x3ff
	v_readlane_b32 s17, v255, 2
	s_barrier
	s_branch .LBB0_665

; #define PG8_STAGE(bufoff, gbase, voff) do { _Pragma("unroll") for (int _i = 0; _i < 2; ++_i) \
;         __builtin_amdgcn_global_load_lds((const unsigned*)((const char*)(gbase) + (voff)[_i]), (LAS unsigned*)(lds + (bufoff) + ldsw + _i * 8192), 16, 0, 0); } while (0)
; #define PG8_WAIT_V(n) asm volatile("s_waitcnt vmcnt(" #n ")" ::: "memory")
; #define PG8_BAR __builtin_amdgcn_s_barrier()
; template <class Epi, class Sched>
; __device__ __forceinline__ void gemm_phase(LAS unsigned char* lds, const Gemm g, const Sched& S, const Epi& E, int wave_id) {
;     ...
;     PG8_STAGE(PG8_SB(0, 0), cB, voffB); PG8_STAGE(PG8_SB(0, 1), cB + hstepB, voffB); PG8_STAGE(PG8_SA(0, 0), cA, voffA); PG8_STAGE(PG8_SA(0, 1), cA + hstepA, voffA);
;     if (wr == 1) PG8_BAR;
;     PG8_WAIT_V(2); PG8_BAR;
;     PG8_STAGE(PG8_SB(1, 0), cB + kstep, voffB); PG8_STAGE(PG8_SA(1, 0), cA + kstep, voffA); PG8_STAGE(PG8_SB(1, 1), cB + hstepB + kstep, voffB);
;     PG8_WAIT_V(6); PG8_BAR;
.LBB0_688:
	s_mov_b64 s[10:11], 0x80
	s_add_i32 m0, s36, 0x18000
	v_lshl_add_u64 v[6:7], v[6:7], 0, s[10:11]
	global_load_lds_dwordx4 v[6:7], off
	v_lshl_add_u64 v[2:3], v[2:3], 0, s[10:11]
	s_add_i32 m0, s36, 0x1a000
	s_add_i32 s48, s36, 0x8000
	s_add_i32 s50, s36, 0xa000
	global_load_lds_dwordx4 v[2:3], off
	v_lshl_add_u64 v[0:1], v[0:1], 0, s[10:11]
	s_mov_b32 m0, s48
	s_add_u32 s4, s30, 0x10080
	global_load_lds_dwordx4 v[0:1], off
	v_lshl_add_u64 v[0:1], v[4:5], 0, s[10:11]
	s_mov_b32 m0, s50
	s_addc_u32 s5, s31, 0
	s_add_i32 s51, s36, 0x1c000
	global_load_lds_dwordx4 v[0:1], off
	s_mov_b32 m0, s51
	s_add_i32 s58, s36, 0x1e000
	global_load_lds_dwordx4 v68, s[4:5]
	v_lshl_add_u64 v[0:1], s[4:5], 0, v[64:65]
	s_mov_b32 m0, s58
	s_movk_i32 s4, 0x3c0
	global_load_lds_dwordx4 v[0:1], off
	s_waitcnt vmcnt(8)
	s_barrier
	v_and_b32_e32 v0, 15, v8
	v_lshrrev_b32_e32 v1, 1, v8
	v_or_b32_e32 v74, s55, v0
	v_and_b32_e32 v1, 24, v1
	v_lshlrev_b32_e32 v2, 6, v74
	v_lshlrev_b32_e32 v3, 1, v1
	v_and_or_b32 v2, v2, s4, v3
	v_lshl_or_b32 v0, v0, 6, v3
	v_lshlrev_b32_e32 v3, 2, v8
	v_and_b32_e32 v3, 32, v3
	v_bitop3_b32 v3, v0, s52, v3 bitop3:0xde
	v_or_b32_e32 v0, s53, v1
	s_cmpk_lt_u32 s80, 0x100
	v_lshlrev_b32_e32 v0, 2, v0
	v_mov_b32_e32 v1, v69
	v_readlane_b32 s16, v255, 1
	s_cselect_b64 s[4:5], -1, 0
	v_lshl_add_u64 v[0:1], s[92:93], 0, v[0:1]
	s_mov_b64 s[12:13], 0x1d400000
	s_add_i32 s59, s66, s16
	v_lshl_add_u64 v[72:73], v[0:1], 0, s[12:13]
	s_mul_i32 s13, s59, 0x30000
	s_mul_hi_i32 s12, s59, 0x30000
	s_add_u32 s13, s92, s13
	s_addc_u32 s14, s93, s12
	v_lshlrev_b32_e32 v4, 2, v74
	s_add_u32 s12, s13, 0x17400000
	v_and_b32_e32 v4, 32, v4
	s_waitcnt vmcnt(6)
	s_addc_u32 s13, s14, 0
	s_add_i32 s64, 0, 0x10000
	s_mov_b32 s22, s66
	s_add_i32 s66, 0, 0x18000
	v_bitop3_b32 v2, v2, s54, v4 bitop3:0xde
	v_readlane_b32 s17, v255, 2
	v_add_u32_e32 v75, s64, v3
	s_add_i32 s64, s64, s44
	v_cndmask_b32_e64 v0, 0, 1, s[4:5]
	v_add_u32_e32 v77, s66, v3
	s_add_i32 s66, s66, s44
	s_mul_hi_i32 s60, s16, 0x30000
	s_mul_i32 s61, s16, 0x30000
	v_add_u32_e32 v76, 0, v2
	s_add_i32 s62, s36, 0xc000
	s_add_i32 s63, s36, 0xe000
	s_mov_b64 s[14:15], 0x100
	s_add_i32 s65, s64, 0x2000
	s_mov_b64 s[16:17], 0x180
	s_add_i32 s67, s66, 0x2000
	v_cmp_ne_u32_e64 s[4:5], 1, v0
	s_mov_b32 s73, s22
	s_mov_b64 s[22:23], s[28:29]
	s_barrier
	s_branch .LBB0_691

; #define PG8_STAGE(bufoff, gbase, voff) do { _Pragma("unroll") for (int _i = 0; _i < 2; ++_i) \
;         __builtin_amdgcn_global_load_lds((const unsigned*)((const char*)(gbase) + (voff)[_i]), (LAS unsigned*)(lds + (bufoff) + ldsw + _i * 8192), 16, 0, 0); } while (0)
; #define PG8_WAIT_V(n) asm volatile("s_waitcnt vmcnt(" #n ")" ::: "memory")
; #define PG8_BAR __builtin_amdgcn_s_barrier()
; template <class Epi, class Sched>
; __device__ __forceinline__ void gemm_phase(LAS unsigned char* lds, const Gemm g, const Sched& S, const Epi& E, int wave_id) {
;     ...
;     PG8_STAGE(PG8_SB(0, 0), cB, voffB); PG8_STAGE(PG8_SB(0, 1), cB + hstepB, voffB); PG8_STAGE(PG8_SA(0, 0), cA, voffA); PG8_STAGE(PG8_SA(0, 1), cA + hstepA, voffA);
;     if (wr == 1) PG8_BAR;
;     PG8_WAIT_V(2); PG8_BAR;
;     PG8_STAGE(PG8_SB(1, 0), cB + kstep, voffB); PG8_STAGE(PG8_SA(1, 0), cA + kstep, voffA); PG8_STAGE(PG8_SB(1, 1), cB + hstepB + kstep, voffB);
;     PG8_WAIT_V(6); PG8_BAR;
.LBB0_717:
	s_mov_b64 s[6:7], 0x80
	v_readlane_b32 s12, v255, 1
	s_add_i32 m0, s29, 0x18000
	v_lshl_add_u64 v[6:7], v[6:7], 0, s[6:7]
	s_ashr_i32 s49, s12, 31
	global_load_lds_dwordx4 v[6:7], off
	v_lshl_add_u64 v[4:5], v[4:5], 0, s[6:7]
	s_add_i32 m0, s29, 0x1a000
	s_add_i32 s50, s29, 0x8000
	s_add_i32 s51, s29, 0xa000
	global_load_lds_dwordx4 v[4:5], off
	v_lshl_add_u64 v[0:1], v[0:1], 0, s[6:7]
	s_mov_b32 m0, s50
	s_add_u32 s10, s34, 0x40080
	global_load_lds_dwordx4 v[0:1], off
	v_lshl_add_u64 v[0:1], v[2:3], 0, s[6:7]
	s_mov_b32 m0, s51
	s_addc_u32 s11, s35, 0
	global_load_lds_dwordx4 v[0:1], off
	s_add_i32 m0, s29, 0x1c000
	s_nop 0
	global_load_lds_dwordx4 v130, s[10:11]
	v_lshl_add_u64 v[0:1], s[10:11], 0, v[134:135]
	s_add_i32 m0, s29, 0x1e000
	s_sext_i32_i8 s58, s8
	global_load_lds_dwordx4 v[0:1], off
	s_waitcnt vmcnt(8)
	s_barrier
	v_and_b32_e32 v0, 15, v8
	v_lshrrev_b32_e32 v1, 1, v8
	v_or_b32_e32 v158, s55, v0
	v_and_b32_e32 v1, 24, v1
	v_lshlrev_b32_e32 v2, 6, v158
	v_lshlrev_b32_e32 v3, 1, v1
	s_movk_i32 s8, 0x3c0
	v_and_or_b32 v2, v2, s8, v3
	v_lshl_or_b32 v0, v0, 6, v3
	v_lshlrev_b32_e32 v3, 2, v8
	v_and_b32_e32 v3, 32, v3
	v_bitop3_b32 v159, v0, s52, v3 bitop3:0xde
	v_lshlrev_b32_e32 v0, 14, v9
	v_and_b32_e32 v0, 0xffff8000, v0
	v_or_b32_e32 v160, s53, v1
	v_lshl_add_u32 v0, v10, 11, v0
	v_and_b32_e32 v1, 1, v9
	s_cmpk_lt_u32 s80, 0x100
	v_lshl_or_b32 v0, v1, 6, v0
	s_cselect_b64 s[8:9], -1, 0
	s_add_u32 s10, s92, 0x1f400000
	v_lshl_add_u32 v136, v11, 1, v0
	v_lshlrev_b32_e32 v0, 14, v12
	v_lshlrev_b32_e32 v4, 2, v158
	s_addc_u32 s11, s93, 0
	v_and_b32_e32 v0, 0xffff8000, v0
	v_readlane_b32 s13, v255, 2
	v_and_b32_e32 v4, 32, v4
	s_mov_b32 s52, s12
	s_waitcnt vmcnt(6)
	s_add_u32 s12, s92, 0xb400000
	v_lshl_add_u32 v0, v13, 11, v0
	v_and_b32_e32 v1, 1, v12
	v_bitop3_b32 v2, v2, s54, v4 bitop3:0xde
	s_addc_u32 s13, s93, 0
	v_lshl_or_b32 v0, v1, 6, v0
	s_add_i32 s53, 0, 0x10000
	s_add_i32 s54, 0, 0x14000
	v_mov_b32_e32 v137, v131
	v_lshl_add_u32 v138, v14, 1, v0
	v_mov_b32_e32 v139, v131
	v_add_u32_e32 v161, s53, v159
	v_add_u32_e32 v162, s54, v159
	v_add_u32_e32 v163, 0, v2
	s_mov_b32 s14, 0x437f0000
	s_mov_b32 s55, 0xb400000
	v_mov_b64_e32 v[140:141], 0x3ff
	s_barrier
	s_branch .LBB0_720

;     __device__ bool next(int i, Unit& u) const { if (r0 + i >= r1) return false; return base.next(r0 + i, u); }
;     __device__ bool next(int i, Unit& u) const { const int L = i * G + c; if (L >= 256) return false; u.pm = L; u.pn = L >> 3; return true; }
; #define PG8_STAGE(bufoff, gbase, voff) do { _Pragma("unroll") for (int _i = 0; _i < 2; ++_i) \
;         __builtin_amdgcn_global_load_lds((const unsigned*)((const char*)(gbase) + (voff)[_i]), (LAS unsigned*)(lds + (bufoff) + ldsw + _i * 8192), 16, 0, 0); } while (0)
; #define PG8_WAIT_V(n) asm volatile("s_waitcnt vmcnt(" #n ")" ::: "memory")
; #define PG8_BAR __builtin_amdgcn_s_barrier()
;     __device__ bool next(int i, Unit& u) const {
;         const long L = (long)i * G + c; if (L >= nwg) return false;
;         int wgid = (int)L; { const int q = nwg / NXCD, r = nwg % NXCD, xcd = wgid % NXCD, off = wgid / NXCD; wgid = (xcd < r ? xcd * (q + 1) : r * (q + 1) + (xcd - r) * q) + off; }
;         const int nig = WGM * nN, gid = wgid / nig, fm = gid * WGM, gsz = (nM - fm) < WGM ? (nM - fm) : WGM;
;         u.pm = fm + ((wgid % nig) % gsz); u.pn = (wgid % nig) / gsz; return true;
; template <class Epi, class Sched>
; __device__ __forceinline__ void gemm_phase(LAS unsigned char* lds, const Gemm g, const Sched& S, const Epi& E, int wave_id) {
;     ...
;     PG8_STAGE(PG8_SB(0, 0), cB, voffB); PG8_STAGE(PG8_SB(0, 1), cB + hstepB, voffB); PG8_STAGE(PG8_SA(0, 0), cA, voffA); PG8_STAGE(PG8_SA(0, 1), cA + hstepA, voffA);
;     if (wr == 1) PG8_BAR;
;     PG8_WAIT_V(2); PG8_BAR;
;     PG8_STAGE(PG8_SB(1, 0), cB + kstep, voffB); PG8_STAGE(PG8_SA(1, 0), cA + kstep, voffA); PG8_STAGE(PG8_SB(1, 1), cB + hstepB + kstep, voffB);
;     PG8_WAIT_V(6); PG8_BAR;
.LBB0_800:
	v_lshrrev_b32_e32 v16, 1, v14
	v_and_b32_e32 v16, 24, v16
	v_and_b32_e32 v15, 15, v14
	v_lshlrev_b32_e32 v17, 1, v16
	v_lshlrev_b32_e32 v14, 2, v14
	v_lshl_or_b32 v156, s8, 6, v15
	v_lshl_or_b32 v15, v15, 6, v17
	s_lshl_b32 s8, s8, 13
	v_and_b32_e32 v14, 32, v14
	v_bitop3_b32 v17, v15, s8, v14 bitop3:0xde
	s_lshl_b32 s8, s97, 5
	s_and_b32 s16, s8, 0x60
	s_lshl_b32 s8, s16, 7
	v_bitop3_b32 v157, v15, s8, v14 bitop3:0xde
	s_mov_b64 s[8:9], 0x80
	s_add_i32 m0, s27, 0x18000
	v_lshl_add_u64 v[6:7], v[6:7], 0, s[8:9]
	global_load_lds_dwordx4 v[6:7], off
	v_lshl_add_u64 v[4:5], v[4:5], 0, s[8:9]
	s_add_i32 m0, s27, 0x1a000
	s_add_i32 s46, s27, 0x8000
	s_add_i32 s47, s27, 0xa000
	global_load_lds_dwordx4 v[4:5], off
	v_lshl_add_u64 v[0:1], v[0:1], 0, s[8:9]
	s_mov_b32 m0, s46
	s_add_u32 s10, s34, 0x40080
	global_load_lds_dwordx4 v[0:1], off
	v_lshl_add_u64 v[0:1], v[2:3], 0, s[8:9]
	s_mov_b32 m0, s47
	s_addc_u32 s11, s35, 0
	global_load_lds_dwordx4 v[0:1], off
	s_add_i32 m0, s27, 0x1c000
	s_nop 0
	global_load_lds_dwordx4 v130, s[10:11]
	s_add_i32 m0, s27, 0x1e000
	s_cmpk_lt_u32 s80, 0x100
	global_load_lds_dwordx4 v134, s[10:11]
	s_waitcnt vmcnt(8)
	s_barrier
	s_cselect_b64 s[10:11], -1, 0
	s_add_u32 s12, s92, 0x1f400000
	s_addc_u32 s13, s93, 0
	s_add_u32 s14, s92, 0xb400000
	s_addc_u32 s15, s93, 0
	s_mul_hi_i32 s17, s4, 3
	s_mul_i32 s4, s4, 3
	s_add_u32 s4, s4, s66
	s_addc_u32 s5, s17, s5
	s_ashr_i32 s17, s4, 31
	s_lshr_b32 s17, s17, 29
	s_add_i32 s17, s4, s17
	s_ashr_i32 s18, s17, 3
	s_and_b32 s17, s17, -8
	s_sub_i32 s17, s4, s17
	s_lshl_b32 s19, s17, 7
	s_cmp_lt_i32 s17, 0
	s_mulk_i32 s17, 0x81
	s_cselect_b32 s17, s17, s19
	s_add_i32 s17, s17, s18
	s_ashr_i32 s18, s17, 31
	s_lshr_b32 s18, s18, 26
	s_add_i32 s18, s17, s18
	s_ashr_i32 s19, s18, 6
	s_lshl_b32 s19, s19, 3
	s_sub_i32 s20, 0x80, s19
	s_min_i32 s20, s20, 8
	s_abs_i32 s22, s20
	v_cvt_f32_u32_e32 v2, s22
	v_mov_b64_e32 v[0:1], 0x400
	v_cmp_lt_i64_e64 s[36:37], s[4:5], v[0:1]
	s_andn2_b32 s18, s18, 63
	v_rcp_iflag_f32_e32 v0, v2
	s_sub_i32 s4, s17, s18
	s_sub_i32 s17, 0, s22
	v_or_b32_e32 v158, s16, v16
	v_mul_f32_e32 v0, 0x4f7ffffe, v0
	v_cvt_u32_f32_e32 v0, v0
	s_abs_i32 s16, s4
	s_xor_b32 s5, s4, s20
	s_ashr_i32 s5, s5, 31
	v_readfirstlane_b32 s18, v0
	s_mul_i32 s17, s17, s18
	s_mul_hi_u32 s17, s18, s17
	s_add_i32 s18, s18, s17
	s_mul_hi_u32 s17, s16, s18
	s_mul_i32 s18, s17, s22
	s_sub_i32 s16, s16, s18
	s_add_i32 s18, s17, 1
	s_sub_i32 s23, s16, s22
	s_cmp_ge_u32 s16, s22
	s_cselect_b32 s17, s18, s17
	v_lshlrev_b32_e32 v0, 14, v8
	s_cselect_b32 s16, s23, s16
	s_add_i32 s18, s17, 1
	v_and_b32_e32 v0, 0xffff8000, v0
	s_cmp_ge_u32 s16, s22
	v_lshl_add_u32 v0, v9, 11, v0
	v_and_b32_e32 v1, 1, v8
	s_cselect_b32 s16, s18, s17
	v_lshl_or_b32 v0, v1, 6, v0
	s_xor_b32 s16, s16, s5
	v_lshl_add_u32 v136, v10, 1, v0
	v_lshlrev_b32_e32 v0, 14, v11
	s_sub_i32 s16, s16, s5
	v_and_b32_e32 v0, 0xffff8000, v0
	s_waitcnt vmcnt(6)
	s_mul_i32 s5, s16, s20
	v_lshl_add_u32 v0, v12, 11, v0
	v_and_b32_e32 v1, 1, v11
	s_sub_i32 s4, s4, s5
	v_lshl_or_b32 v0, v1, 6, v0
	s_add_i32 s48, 0, 0x10000
	s_add_i32 s49, 0, 0x14000
	s_add_i32 s18, s19, s4
	v_mov_b32_e32 v137, v131
	v_lshl_add_u32 v138, v13, 1, v0
	v_mov_b32_e32 v139, v131
	v_add_u32_e32 v159, s48, v157
	v_add_u32_e32 v160, s49, v157
	v_add_u32_e32 v161, 0, v17
	s_mov_b32 s20, 0x437f0000
	s_mov_b32 s50, 0xb400000
	s_barrier
	s_branch .LBB0_803

;     __device__ bool next(int i, Unit& u) const { if (r0 + i >= r1) return false; return base.next(r0 + i, u); }
;     __device__ bool next(int i, Unit& u) const { const int L = i * G + c; if (L >= 256) return false; u.pm = L; u.pn = L >> 3; return true; }
; #define PG8_STAGE(bufoff, gbase, voff) do { _Pragma("unroll") for (int _i = 0; _i < 2; ++_i) \
;         __builtin_amdgcn_global_load_lds((const unsigned*)((const char*)(gbase) + (voff)[_i]), (LAS unsigned*)(lds + (bufoff) + ldsw + _i * 8192), 16, 0, 0); } while (0)
; #define PG8_WAIT_V(n) asm volatile("s_waitcnt vmcnt(" #n ")" ::: "memory")
; #define PG8_BAR __builtin_amdgcn_s_barrier()
;     __device__ bool next(int i, Unit& u) const {
;         const long L = (long)i * G + c; if (L >= nwg) return false;
;         int wgid = (int)L; { const int q = nwg / NXCD, r = nwg % NXCD, xcd = wgid % NXCD, off = wgid / NXCD; wgid = (xcd < r ? xcd * (q + 1) : r * (q + 1) + (xcd - r) * q) + off; }
;         const int nig = WGM * nN, gid = wgid / nig, fm = gid * WGM, gsz = (nM - fm) < WGM ? (nM - fm) : WGM;
;         u.pm = fm + ((wgid % nig) % gsz); u.pn = (wgid % nig) / gsz; return true;
; template <class Epi, class Sched>
; __device__ __forceinline__ void gemm_phase(LAS unsigned char* lds, const Gemm g, const Sched& S, const Epi& E, int wave_id) {
;     ...
;     PG8_STAGE(PG8_SB(0, 0), cB, voffB); PG8_STAGE(PG8_SB(0, 1), cB + hstepB, voffB); PG8_STAGE(PG8_SA(0, 0), cA, voffA); PG8_STAGE(PG8_SA(0, 1), cA + hstepA, voffA);
;     if (wr == 1) PG8_BAR;
;     PG8_WAIT_V(2); PG8_BAR;
;     PG8_STAGE(PG8_SB(1, 0), cB + kstep, voffB); PG8_STAGE(PG8_SA(1, 0), cA + kstep, voffA); PG8_STAGE(PG8_SB(1, 1), cB + hstepB + kstep, voffB);
;     PG8_WAIT_V(6); PG8_BAR;
.LBB0_859:
	v_lshrrev_b32_e32 v16, 1, v14
	v_and_b32_e32 v16, 24, v16
	v_and_b32_e32 v15, 15, v14
	v_lshlrev_b32_e32 v17, 1, v16
	v_lshlrev_b32_e32 v14, 2, v14
	v_lshl_or_b32 v156, s8, 6, v15
	v_lshl_or_b32 v15, v15, 6, v17
	s_lshl_b32 s8, s8, 13
	v_and_b32_e32 v14, 32, v14
	v_bitop3_b32 v17, v15, s8, v14 bitop3:0xde
	s_lshl_b32 s8, s97, 5
	s_and_b32 s16, s8, 0x60
	s_lshl_b32 s8, s16, 7
	v_bitop3_b32 v157, v15, s8, v14 bitop3:0xde
	s_mov_b64 s[8:9], 0x80
	s_add_i32 m0, s27, 0x18000
	v_lshl_add_u64 v[6:7], v[6:7], 0, s[8:9]
	global_load_lds_dwordx4 v[6:7], off
	v_lshl_add_u64 v[4:5], v[4:5], 0, s[8:9]
	s_add_i32 m0, s27, 0x1a000
	s_add_i32 s41, s27, 0x8000
	s_add_i32 s42, s27, 0xa000
	global_load_lds_dwordx4 v[4:5], off
	v_lshl_add_u64 v[0:1], v[0:1], 0, s[8:9]
	s_mov_b32 m0, s41
	s_add_u32 s10, s34, 0x40080
	global_load_lds_dwordx4 v[0:1], off
	v_lshl_add_u64 v[0:1], v[2:3], 0, s[8:9]
	s_mov_b32 m0, s42
	s_addc_u32 s11, s35, 0
	global_load_lds_dwordx4 v[0:1], off
	s_add_i32 m0, s27, 0x1c000
	s_nop 0
	global_load_lds_dwordx4 v130, s[10:11]
	s_add_i32 m0, s27, 0x1e000
	s_cmpk_lt_u32 s80, 0x100
	global_load_lds_dwordx4 v134, s[10:11]
	s_waitcnt vmcnt(8)
	s_barrier
	s_cselect_b64 s[10:11], -1, 0
	s_add_u32 s12, s92, 0x1f400000
	s_addc_u32 s13, s93, 0
	s_add_u32 s14, s92, 0xb400000
	s_addc_u32 s15, s93, 0
	s_mul_hi_i32 s17, s4, 3
	s_mul_i32 s4, s4, 3
	s_add_u32 s4, s4, s66
	s_addc_u32 s5, s17, s5
	s_ashr_i32 s17, s4, 31
	s_lshr_b32 s17, s17, 29
	s_add_i32 s17, s4, s17
	s_ashr_i32 s18, s17, 3
	s_and_b32 s17, s17, -8
	s_sub_i32 s17, s4, s17
	s_lshl_b32 s19, s17, 7
	s_cmp_lt_i32 s17, 0
	s_mulk_i32 s17, 0x81
	s_cselect_b32 s17, s17, s19
	s_add_i32 s17, s17, s18
	s_ashr_i32 s18, s17, 31
	s_lshr_b32 s18, s18, 26
	s_add_i32 s18, s17, s18
	s_ashr_i32 s19, s18, 6
	s_lshl_b32 s19, s19, 3
	s_sub_i32 s20, 0x80, s19
	s_min_i32 s20, s20, 8
	s_abs_i32 s22, s20
	v_cvt_f32_u32_e32 v2, s22
	v_mov_b64_e32 v[0:1], 0x400
	v_cmp_lt_i64_e64 s[36:37], s[4:5], v[0:1]
	s_andn2_b32 s18, s18, 63
	v_rcp_iflag_f32_e32 v0, v2
	s_sub_i32 s4, s17, s18
	s_sub_i32 s17, 0, s22
	v_or_b32_e32 v158, s16, v16
	v_mul_f32_e32 v0, 0x4f7ffffe, v0
	v_cvt_u32_f32_e32 v0, v0
	s_abs_i32 s16, s4
	s_xor_b32 s5, s4, s20
	s_ashr_i32 s5, s5, 31
	v_readfirstlane_b32 s18, v0
	s_mul_i32 s17, s17, s18
	s_mul_hi_u32 s17, s18, s17
	s_add_i32 s18, s18, s17
	s_mul_hi_u32 s17, s16, s18
	s_mul_i32 s18, s17, s22
	s_sub_i32 s16, s16, s18
	s_add_i32 s18, s17, 1
	s_sub_i32 s23, s16, s22
	s_cmp_ge_u32 s16, s22
	s_cselect_b32 s17, s18, s17
	v_lshlrev_b32_e32 v0, 14, v8
	s_cselect_b32 s16, s23, s16
	s_add_i32 s18, s17, 1
	v_and_b32_e32 v0, 0xffff8000, v0
	s_cmp_ge_u32 s16, s22
	v_lshl_add_u32 v0, v9, 11, v0
	v_and_b32_e32 v1, 1, v8
	s_cselect_b32 s16, s18, s17
	v_lshl_or_b32 v0, v1, 6, v0
	s_xor_b32 s16, s16, s5
	v_lshl_add_u32 v136, v10, 1, v0
	v_lshlrev_b32_e32 v0, 14, v11
	s_sub_i32 s16, s16, s5
	v_and_b32_e32 v0, 0xffff8000, v0
	s_waitcnt vmcnt(6)
	s_mul_i32 s5, s16, s20
	v_lshl_add_u32 v0, v12, 11, v0
	v_and_b32_e32 v1, 1, v11
	s_sub_i32 s4, s4, s5
	v_lshl_or_b32 v0, v1, 6, v0
	s_add_i32 s43, 0, 0x10000
	s_add_i32 s44, 0, 0x14000
	s_add_i32 s18, s19, s4
	v_mov_b32_e32 v137, v131
	v_lshl_add_u32 v138, v13, 1, v0
	v_mov_b32_e32 v139, v131
	v_add_u32_e32 v159, s43, v157
	v_add_u32_e32 v160, s44, v157
	v_add_u32_e32 v161, 0, v17
	s_mov_b32 s20, 0x437f0000
	s_mov_b32 s45, 0xb400000
	s_barrier
	s_branch .LBB0_862

; #define PG8_STAGE(bufoff, gbase, voff) do { _Pragma("unroll") for (int _i = 0; _i < 2; ++_i) \
;         __builtin_amdgcn_global_load_lds((const unsigned*)((const char*)(gbase) + (voff)[_i]), (LAS unsigned*)(lds + (bufoff) + ldsw + _i * 8192), 16, 0, 0); } while (0)
; #define PG8_WAIT_V(n) asm volatile("s_waitcnt vmcnt(" #n ")" ::: "memory")
; #define PG8_BAR __builtin_amdgcn_s_barrier()
; template <class Epi, class Sched>
; __device__ __forceinline__ void gemm_phase(LAS unsigned char* lds, const Gemm g, const Sched& S, const Epi& E, int wave_id) {
;     ...
;     PG8_STAGE(PG8_SB(0, 0), cB, voffB); PG8_STAGE(PG8_SB(0, 1), cB + hstepB, voffB); PG8_STAGE(PG8_SA(0, 0), cA, voffA); PG8_STAGE(PG8_SA(0, 1), cA + hstepA, voffA);
;     if (wr == 1) PG8_BAR;
;     PG8_WAIT_V(2); PG8_BAR;
;     PG8_STAGE(PG8_SB(1, 0), cB + kstep, voffB); PG8_STAGE(PG8_SA(1, 0), cA + kstep, voffA); PG8_STAGE(PG8_SB(1, 1), cB + hstepB + kstep, voffB);
;     PG8_WAIT_V(6); PG8_BAR;
.LBB0_930:
	s_lshl_b32 s4, s97, 5
	s_mov_b64 s[12:13], 0x80
	s_and_b32 s6, s4, 0x60
	s_add_i32 m0, s38, 0x18000
	v_lshl_add_u64 v[6:7], v[6:7], 0, s[12:13]
	s_lshl_b32 s7, s6, 7
	global_load_lds_dwordx4 v[6:7], off
	v_lshl_add_u64 v[4:5], v[4:5], 0, s[12:13]
	s_add_i32 m0, s38, 0x1a000
	s_add_i32 s43, s38, 0x8000
	s_add_i32 s44, s38, 0xa000
	global_load_lds_dwordx4 v[4:5], off
	v_lshl_add_u64 v[0:1], v[0:1], 0, s[12:13]
	s_mov_b32 m0, s43
	s_add_u32 s4, s34, 0x18080
	global_load_lds_dwordx4 v[0:1], off
	v_lshl_add_u64 v[0:1], v[2:3], 0, s[12:13]
	s_mov_b32 m0, s44
	s_addc_u32 s5, s35, 0
	global_load_lds_dwordx4 v[0:1], off
	s_add_i32 m0, s38, 0x1c000
	s_nop 0
	global_load_lds_dwordx4 v132, s[4:5]
	v_lshl_add_u64 v[0:1], s[4:5], 0, v[128:129]
	s_add_i32 m0, s38, 0x1e000
	s_cmpk_lt_u32 s80, 0x100
	global_load_lds_dwordx4 v[0:1], off
	s_waitcnt vmcnt(8)
	s_barrier
	v_and_b32_e32 v1, 15, v8
	v_lshrrev_b32_e32 v0, 1, v8
	v_and_b32_e32 v2, 24, v0
	v_lshlrev_b32_e32 v3, 6, v1
	v_lshl_or_b32 v3, v2, 1, v3
	s_cselect_b64 s[4:5], -1, 0
	v_or_b32_e32 v2, s6, v2
	s_lshl_b32 s6, s3, 10
	v_lshlrev_b32_e32 v4, 2, v8
	s_add_u32 s14, s92, 0x1c400000
	v_readlane_b32 s18, v255, 1
	v_and_b32_e32 v4, 32, v4
	s_addc_u32 s15, s93, 0
	s_add_i32 s45, s66, s18
	v_bitop3_b32 v5, v3, s33, v4 bitop3:0xde
	v_bitop3_b32 v3, v3, s7, v4 bitop3:0xde
	v_lshrrev_b32_e32 v2, 4, v2
	v_lshlrev_b32_e32 v1, 4, v1
	s_mul_i32 s7, s45, 0x30000
	v_or3_b32 v139, v1, s6, v2
	s_mul_hi_i32 s6, s45, 0x30000
	s_add_u32 s7, s92, s7
	s_addc_u32 s6, s93, s6
	s_add_u32 s16, s7, 0x17400000
	s_waitcnt vmcnt(6)
	s_addc_u32 s17, s6, 0
	s_add_i32 s50, 0, 0x10000
	s_add_i32 s52, 0, 0x14000
	s_add_i32 s54, 0, 0x18000
	s_add_i32 s58, 0, 0x1c000
	v_and_b32_e32 v0, 8, v0
	v_readlane_b32 s19, v255, 2
	v_add_u32_e32 v147, s50, v3
	v_add_u32_e32 v148, s52, v3
	v_cndmask_b32_e64 v1, 0, 1, s[4:5]
	s_add_i32 s50, s50, s2
	s_add_i32 s52, s52, s2
	v_add_u32_e32 v149, s54, v3
	v_add_u32_e32 v150, s58, v3
	s_add_i32 s54, s54, s2
	s_add_i32 s58, s58, s2
	v_add_u32_e32 v138, 0, v5
	v_or_b32_e32 v151, 0x100, v139
	v_or_b32_e32 v254, 0x200, v139
	v_or_b32_e32 v142, 0x300, v139
	v_add_u32_e32 v143, 0x800, v139
	v_add_u32_e32 v144, 0x900, v139
	v_add_u32_e32 v145, 0xa00, v139
	v_add_u32_e32 v146, 0xb00, v139
	s_mul_hi_i32 s46, s18, 0x30000
	s_mul_i32 s47, s18, 0x30000
	s_add_i32 s48, s38, 0xc000
	s_add_i32 s49, s38, 0xe000
	s_mov_b64 s[18:19], 0x100
	s_mov_b64 s[20:21], 0x180
	s_mov_b64 s[22:23], 0x200
	s_mov_b64 s[24:25], 0x280
	v_lshlrev_b32_e32 v136, 1, v0
	s_add_i32 s51, s50, 0x2000
	s_add_i32 s53, s52, 0x2000
	s_add_i32 s55, s54, 0x2000
	s_add_i32 s59, s58, 0x2000
	v_cmp_ne_u32_e64 s[4:5], 1, v1
	s_mov_b32 s62, s66
	s_mov_b64 s[26:27], s[30:31]
	s_barrier
	s_waitcnt vmcnt(0)
	s_branch .LBB0_933

; #define PG8_STAGE(bufoff, gbase, voff) do { _Pragma("unroll") for (int _i = 0; _i < 2; ++_i) \
;         __builtin_amdgcn_global_load_lds((const unsigned*)((const char*)(gbase) + (voff)[_i]), (LAS unsigned*)(lds + (bufoff) + ldsw + _i * 8192), 16, 0, 0); } while (0)
; #define PG8_WAIT_V(n) asm volatile("s_waitcnt vmcnt(" #n ")" ::: "memory")
; #define PG8_BAR __builtin_amdgcn_s_barrier()
; template <class Epi, class Sched>
; __device__ __forceinline__ void gemm_phase(LAS unsigned char* lds, const Gemm g, const Sched& S, const Epi& E, int wave_id) {
;     ...
;     PG8_STAGE(PG8_SB(0, 0), cB, voffB); PG8_STAGE(PG8_SB(0, 1), cB + hstepB, voffB); PG8_STAGE(PG8_SA(0, 0), cA, voffA); PG8_STAGE(PG8_SA(0, 1), cA + hstepA, voffA);
;     if (wr == 1) PG8_BAR;
;     PG8_WAIT_V(2); PG8_BAR;
;     PG8_STAGE(PG8_SB(1, 0), cB + kstep, voffB); PG8_STAGE(PG8_SA(1, 0), cA + kstep, voffA); PG8_STAGE(PG8_SB(1, 1), cB + hstepB + kstep, voffB);
;     PG8_WAIT_V(6); PG8_BAR;
.LBB0_950:
	s_add_u32 s42, s92, 0x13400000
	s_mov_b64 s[10:11], 0x80
	s_addc_u32 s43, s93, 0
	s_bfe_u32 s5, s80, 0x20006
	s_add_i32 m0, s37, 0x18000
	v_lshl_add_u64 v[6:7], v[6:7], 0, s[10:11]
	s_lshl_b32 s44, s3, 6
	s_lshl_b32 s14, s5, 12
	global_load_lds_dwordx4 v[6:7], off
	v_lshl_add_u64 v[4:5], v[4:5], 0, s[10:11]
	s_add_i32 m0, s37, 0x1a000
	s_add_i32 s45, s37, 0x8000
	s_add_i32 s46, s37, 0xa000
	global_load_lds_dwordx4 v[4:5], off
	v_lshl_add_u64 v[0:1], v[0:1], 0, s[10:11]
	s_mov_b32 m0, s45
	s_add_u32 s12, s26, 0x40080
	global_load_lds_dwordx4 v[0:1], off
	v_lshl_add_u64 v[0:1], v[2:3], 0, s[10:11]
	s_mov_b32 m0, s46
	s_addc_u32 s13, s27, 0
	global_load_lds_dwordx4 v[0:1], off
	s_add_i32 m0, s37, 0x1c000
	s_nop 0
	global_load_lds_dwordx4 v130, s[12:13]
	v_lshl_add_u64 v[0:1], s[12:13], 0, v[134:135]
	s_add_i32 m0, s37, 0x1e000
	v_and_b32_e32 v2, 15, v8
	global_load_lds_dwordx4 v[0:1], off
	s_waitcnt vmcnt(8)
	s_barrier
	v_bfe_u32 v1, v8, 4, 2
	v_lshrrev_b32_e32 v0, 4, v8
	v_lshlrev_b32_e32 v1, 4, v1
	v_lshlrev_b32_e32 v4, 2, v8
	v_lshl_or_b32 v3, v2, 6, v1
	v_and_b32_e32 v4, 32, v4
	v_bfe_u32 v0, v0, 1, 1
	v_bitop3_b32 v5, v3, s33, v4 bitop3:0xde
	v_bitop3_b32 v150, v3, s14, v4 bitop3:0xde
	v_lshl_or_b32 v0, s5, 1, v0
	v_and_or_b32 v3, v1, 16, v2
	v_lshlrev_b32_e32 v136, 4, v3
	v_mul_u32_u24_e32 v3, 0x210, v0
	v_lshlrev_b32_e32 v138, 11, v0
	v_lshlrev_b32_e32 v0, 14, v9
	v_and_b32_e32 v0, 0xffff8000, v0
	s_cmpk_lt_u32 s80, 0x100
	s_mul_i32 s14, s3, 0x2100
	v_lshl_add_u32 v0, v10, 11, v0
	v_and_b32_e32 v6, 1, v9
	s_cselect_b64 s[12:13], -1, 0
	s_add_i32 s14, s14, 0
	v_lshl_or_b32 v0, v6, 6, v0
	s_lshl_b32 s5, s5, 6
	s_add_i32 s14, s14, 0x20000
	v_lshl_add_u32 v142, v11, 1, v0
	v_lshlrev_b32_e32 v0, 14, v12
	s_add_i32 s5, s5, s14
	v_and_b32_e32 v0, 0xffff8000, v0
	s_sext_i32_i8 s23, s4
	s_waitcnt vmcnt(6)
	s_movk_i32 s4, 0x210
	v_mov_b32_e32 v4, s5
	v_lshl_add_u32 v0, v13, 11, v0
	v_and_b32_e32 v6, 1, v12
	v_readlane_b32 s16, v255, 1
	v_mad_u32_u24 v2, v2, s4, v4
	v_add_u32_e32 v4, s14, v136
	v_lshl_or_b32 v0, v6, 6, v0
	s_add_i32 s47, 0, 0x10000
	s_add_i32 s48, 0, 0x14000
	v_mov_b32_e32 v137, v131
	s_ashr_i32 s3, s16, 31
	s_mov_b32 s33, s16
	v_mov_b32_e32 v139, v131
	v_or_b32_e32 v140, 0x4000, v138
	v_mov_b32_e32 v141, v131
	v_mov_b32_e32 v143, v131
	v_lshl_add_u32 v144, v14, 1, v0
	v_mov_b32_e32 v145, v131
	v_mov_b64_e32 v[146:147], 0x200
	v_mov_b64_e32 v[148:149], 0x1ff
	v_add_u32_e32 v151, s47, v150
	v_add_u32_e32 v152, s48, v150
	v_add_u32_e32 v153, 0, v5
	v_add_u32_e32 v154, v2, v1
	v_add_u32_e32 v155, v4, v3
	s_barrier
	v_readlane_b32 s17, v255, 2
	s_waitcnt vmcnt(0)
	s_branch .LBB0_953

; #define PG8_STAGE(bufoff, gbase, voff) do { _Pragma("unroll") for (int _i = 0; _i < 2; ++_i) \
;         __builtin_amdgcn_global_load_lds((const unsigned*)((const char*)(gbase) + (voff)[_i]), (LAS unsigned*)(lds + (bufoff) + ldsw + _i * 8192), 16, 0, 0); } while (0)
; #define PG8_WAIT_V(n) asm volatile("s_waitcnt vmcnt(" #n ")" ::: "memory")
; #define PG8_BAR __builtin_amdgcn_s_barrier()
; template <class Epi, class Sched>
; __device__ __forceinline__ void gemm_phase(LAS unsigned char* lds, const Gemm g, const Sched& S, const Epi& E, int wave_id) {
;     ...
;     PG8_STAGE(PG8_SB(0, 0), cB, voffB); PG8_STAGE(PG8_SB(0, 1), cB + hstepB, voffB); PG8_STAGE(PG8_SA(0, 0), cA, voffA); PG8_STAGE(PG8_SA(0, 1), cA + hstepA, voffA);
;     if (wr == 1) PG8_BAR;
;     PG8_WAIT_V(2); PG8_BAR;
;     PG8_STAGE(PG8_SB(1, 0), cB + kstep, voffB); PG8_STAGE(PG8_SA(1, 0), cA + kstep, voffA); PG8_STAGE(PG8_SB(1, 1), cB + hstepB + kstep, voffB);
;     PG8_WAIT_V(6); PG8_BAR;
.LBB0_1031:
	s_lshl_b32 s10, s97, 5
	s_and_b32 s15, s10, 0x60
	s_mov_b64 s[10:11], 0x80
	s_add_i32 m0, s25, 0x18000
	v_lshl_add_u64 v[6:7], v[6:7], 0, s[10:11]
	s_lshl_b32 s14, s5, 13
	s_lshl_b32 s16, s15, 7
	global_load_lds_dwordx4 v[6:7], off
	v_lshl_add_u64 v[4:5], v[4:5], 0, s[10:11]
	s_add_i32 m0, s25, 0x1a000
	s_add_i32 s41, s25, 0x8000
	s_add_i32 s42, s25, 0xa000
	global_load_lds_dwordx4 v[4:5], off
	v_lshl_add_u64 v[0:1], v[0:1], 0, s[10:11]
	s_mov_b32 m0, s41
	s_add_u32 s12, s28, 0x20080
	global_load_lds_dwordx4 v[0:1], off
	v_lshl_add_u64 v[0:1], v[2:3], 0, s[10:11]
	s_mov_b32 m0, s42
	s_addc_u32 s13, s29, 0
	global_load_lds_dwordx4 v[0:1], off
	s_add_i32 m0, s25, 0x1c000
	s_nop 0
	global_load_lds_dwordx4 v170, s[12:13]
	v_lshl_add_u64 v[0:1], s[12:13], 0, v[174:175]
	s_add_i32 m0, s25, 0x1e000
	s_cmpk_lt_u32 s80, 0x100
	global_load_lds_dwordx4 v[0:1], off
	s_waitcnt vmcnt(8)
	s_barrier
	v_lshrrev_b32_e32 v0, 1, v8
	v_and_b32_e32 v2, 24, v0
	s_sext_i32_i8 s47, s4
	v_and_b32_e32 v1, 15, v8
	v_lshlrev_b32_e32 v0, 1, v2
	v_lshlrev_b32_e32 v3, 2, v8
	s_cselect_b64 s[12:13], -1, 0
	s_lshl_b32 s4, s15, 1
	v_lshl_or_b32 v198, s5, 6, v1
	v_lshl_or_b32 v1, v1, 6, v0
	v_and_b32_e32 v3, 32, v3
	s_add_u32 s4, s92, s4
	v_bitop3_b32 v4, v1, s14, v3 bitop3:0xde
	v_bitop3_b32 v199, v1, s16, v3 bitop3:0xde
	s_addc_u32 s5, s93, 0
	v_mov_b32_e32 v1, v171
	v_lshl_add_u64 v[0:1], s[4:5], 0, v[0:1]
	s_mov_b64 s[4:5], 0x1a400000
	v_lshl_add_u64 v[176:177], v[0:1], 0, s[4:5]
	v_lshlrev_b32_e32 v0, 13, v9
	v_and_b32_e32 v0, 0xffffc000, v0
	v_lshl_add_u32 v0, v10, 10, v0
	v_and_b32_e32 v1, 1, v9
	v_lshl_or_b32 v0, v1, 6, v0
	v_lshl_add_u32 v178, v11, 1, v0
	v_lshlrev_b32_e32 v0, 13, v12
	v_and_b32_e32 v0, 0xffffc000, v0
	s_waitcnt vmcnt(6)
	s_add_u32 s14, s92, 0xf400000
	v_lshl_add_u32 v0, v13, 10, v0
	v_and_b32_e32 v1, 1, v12
	v_or_b32_e32 v200, s15, v2
	s_addc_u32 s15, s93, 0
	v_readlane_b32 s4, v255, 1
	v_lshl_or_b32 v0, v1, 6, v0
	s_add_i32 s45, 0, 0x10000
	s_add_i32 s46, 0, 0x14000
	s_ashr_i32 s43, s4, 31
	s_mov_b32 s44, s4
	v_mov_b32_e32 v179, v171
	v_lshl_add_u32 v180, v14, 1, v0
	v_mov_b32_e32 v181, v171
	v_mov_b64_e32 v[182:183], 0x200
	v_mov_b64_e32 v[184:185], 0x1ff
	v_add_u32_e32 v201, s45, v199
	v_add_u32_e32 v202, s46, v199
	v_add_u32_e32 v203, 0, v4
	s_barrier
	v_readlane_b32 s5, v255, 2
	s_branch .LBB0_1034

; #define PG8_STAGE(bufoff, gbase, voff) do { _Pragma("unroll") for (int _i = 0; _i < 2; ++_i) \
;         __builtin_amdgcn_global_load_lds((const unsigned*)((const char*)(gbase) + (voff)[_i]), (LAS unsigned*)(lds + (bufoff) + ldsw + _i * 8192), 16, 0, 0); } while (0)
; #define PG8_WAIT_V(n) asm volatile("s_waitcnt vmcnt(" #n ")" ::: "memory")
; #define PG8_BAR __builtin_amdgcn_s_barrier()
; template <class Epi, class Sched>
; __device__ __forceinline__ void gemm_phase(LAS unsigned char* lds, const Gemm g, const Sched& S, const Epi& E, int wave_id) {
;     ...
;     PG8_STAGE(PG8_SB(0, 0), cB, voffB); PG8_STAGE(PG8_SB(0, 1), cB + hstepB, voffB); PG8_STAGE(PG8_SA(0, 0), cA, voffA); PG8_STAGE(PG8_SA(0, 1), cA + hstepA, voffA);
;     if (wr == 1) PG8_BAR;
;     PG8_WAIT_V(2); PG8_BAR;
;     PG8_STAGE(PG8_SB(1, 0), cB + kstep, voffB); PG8_STAGE(PG8_SA(1, 0), cA + kstep, voffA); PG8_STAGE(PG8_SB(1, 1), cB + hstepB + kstep, voffB);
;     PG8_WAIT_V(6); PG8_BAR;
.LBB0_1136:
	s_mov_b64 s[12:13], 0x80
	s_bfe_u32 s16, s80, 0x20006
	s_add_i32 m0, s38, 0x18000
	v_lshl_add_u64 v[6:7], v[6:7], 0, s[12:13]
	s_lshl_b32 s43, s5, 6
	s_lshl_b32 s18, s5, 13
	s_lshl_b32 s19, s16, 5
	s_lshl_b32 s20, s16, 12
	global_load_lds_dwordx4 v[6:7], off
	v_lshl_add_u64 v[4:5], v[4:5], 0, s[12:13]
	s_add_i32 m0, s38, 0x1a000
	s_add_i32 s44, s38, 0x8000
	s_add_i32 s45, s38, 0xa000
	global_load_lds_dwordx4 v[4:5], off
	v_lshl_add_u64 v[0:1], v[0:1], 0, s[12:13]
	s_mov_b32 m0, s44
	s_add_u32 s14, s30, 0x20080
	global_load_lds_dwordx4 v[0:1], off
	v_lshl_add_u64 v[0:1], v[2:3], 0, s[12:13]
	s_mov_b32 m0, s45
	s_addc_u32 s15, s31, 0
	global_load_lds_dwordx4 v[0:1], off
	s_add_i32 m0, s38, 0x1c000
	s_nop 0
	global_load_lds_dwordx4 v154, s[14:15]
	v_lshl_add_u64 v[0:1], s[14:15], 0, v[158:159]
	s_add_i32 m0, s38, 0x1e000
	s_cmpk_lt_u32 s80, 0x100
	global_load_lds_dwordx4 v[0:1], off
	s_waitcnt vmcnt(8)
	s_barrier
	s_sext_i32_i8 s27, s4
	v_bfe_u32 v1, v9, 4, 2
	s_cselect_b64 s[14:15], -1, 0
	s_lshl_b32 s4, s16, 6
	v_and_b32_e32 v204, 15, v9
	v_lshlrev_b32_e32 v2, 4, v1
	v_lshlrev_b32_e32 v4, 2, v9
	s_add_u32 s46, s92, 0xb400000
	v_lshl_or_b32 v3, v204, 6, v2
	v_and_b32_e32 v4, 32, v4
	s_addc_u32 s47, s93, 0
	v_bitop3_b32 v5, v3, s18, v4 bitop3:0xde
	v_bitop3_b32 v205, v3, s20, v4 bitop3:0xde
	s_add_u32 s48, s92, 0x13400000
	v_lshlrev_b32_e32 v4, 13, v8
	s_addc_u32 s49, s93, 0
	v_and_b32_e32 v4, 0xffffc000, v4
	s_mulk_i32 s5, 0x2100
	s_add_u32 s50, s92, 0x7400000
	v_lshl_add_u32 v4, v10, 10, v4
	v_and_b32_e32 v6, 1, v8
	v_lshrrev_b32_e32 v0, 4, v9
	s_addc_u32 s51, s93, 0
	s_add_i32 s5, s5, 0
	v_lshl_or_b32 v4, v6, 6, v4
	v_bfe_u32 v0, v0, 1, 1
	s_add_i32 s5, s5, 0x20000
	v_lshl_add_u32 v170, v11, 1, v4
	v_lshlrev_b32_e32 v4, 13, v12
	v_lshl_or_b32 v162, v1, 3, s19
	v_lshl_or_b32 v0, s16, 1, v0
	v_and_or_b32 v1, v2, 16, v204
	s_add_i32 s4, s4, s5
	v_and_b32_e32 v4, 0xffffc000, v4
	s_waitcnt vmcnt(6)
	v_lshlrev_b32_e32 v164, 4, v1
	s_movk_i32 s16, 0x210
	v_mul_u32_u24_e32 v1, 0x210, v0
	v_lshlrev_b32_e32 v166, 11, v0
	v_mov_b32_e32 v0, s4
	v_lshl_add_u32 v4, v13, 10, v4
	v_and_b32_e32 v6, 1, v12
	v_mad_u32_u24 v0, v204, s16, v0
	v_add_u32_e32 v3, s5, v164
	v_readlane_b32 s4, v255, 1
	v_lshl_or_b32 v4, v6, 6, v4
	s_add_i32 s54, 0, 0x10000
	s_add_i32 s55, 0, 0x14000
	v_mov_b32_e32 v163, v161
	v_mov_b32_e32 v165, v161
	v_mov_b32_e32 v167, v161
	v_or_b32_e32 v168, 0x4000, v166
	v_mov_b32_e32 v169, v161
	s_ashr_i32 s52, s4, 31
	s_mov_b32 s53, s4
	v_mov_b32_e32 v171, v161
	v_lshl_add_u32 v172, v14, 1, v4
	v_mov_b32_e32 v173, v161
	v_mov_b64_e32 v[174:175], 0x200
	v_mov_b64_e32 v[176:177], 0x1ff
	v_add_u32_e32 v206, s54, v205
	v_add_u32_e32 v207, s55, v205
	v_add_u32_e32 v208, 0, v5
	v_lshlrev_b32_e32 v160, 1, v162
	s_mov_b32 s16, 0x3b808081
	v_add_u32_e32 v209, v0, v2
	v_add_u32_e32 v210, v3, v1
	s_barrier
	v_readlane_b32 s5, v255, 2
	s_branch .LBB0_1139

; #define PG8_STAGE(bufoff, gbase, voff) do { _Pragma("unroll") for (int _i = 0; _i < 2; ++_i) \
;         __builtin_amdgcn_global_load_lds((const unsigned*)((const char*)(gbase) + (voff)[_i]), (LAS unsigned*)(lds + (bufoff) + ldsw + _i * 8192), 16, 0, 0); } while (0)
; #define PG8_WAIT_V(n) asm volatile("s_waitcnt vmcnt(" #n ")" ::: "memory")
; #define PG8_BAR __builtin_amdgcn_s_barrier()
; template <class Epi, class Sched>
; __device__ __forceinline__ void gemm_phase(LAS unsigned char* lds, const Gemm g, const Sched& S, const Epi& E, int wave_id) {
;     ...
;     PG8_STAGE(PG8_SB(0, 0), cB, voffB); PG8_STAGE(PG8_SB(0, 1), cB + hstepB, voffB); PG8_STAGE(PG8_SA(0, 0), cA, voffA); PG8_STAGE(PG8_SA(0, 1), cA + hstepA, voffA);
;     if (wr == 1) PG8_BAR;
;     PG8_WAIT_V(2); PG8_BAR;
;     PG8_STAGE(PG8_SB(1, 0), cB + kstep, voffB); PG8_STAGE(PG8_SA(1, 0), cA + kstep, voffA); PG8_STAGE(PG8_SB(1, 1), cB + hstepB + kstep, voffB);
;     PG8_WAIT_V(6); PG8_BAR;
.LBB0_1241:
	s_mov_b64 s[16:17], 0x80
	s_add_i32 m0, s49, 0x18000
	v_lshl_add_u64 v[6:7], v[6:7], 0, s[16:17]
	global_load_lds_dwordx4 v[6:7], off
	v_lshl_add_u64 v[4:5], v[4:5], 0, s[16:17]
	s_add_i32 m0, s49, 0x1a000
	s_add_i32 s54, s49, 0x8000
	s_add_i32 s55, s49, 0xa000
	global_load_lds_dwordx4 v[4:5], off
	v_lshl_add_u64 v[0:1], v[0:1], 0, s[16:17]
	s_mov_b32 m0, s54
	s_add_u32 s6, s36, 0x40080
	global_load_lds_dwordx4 v[0:1], off
	v_lshl_add_u64 v[0:1], v[2:3], 0, s[16:17]
	s_mov_b32 m0, s55
	s_addc_u32 s7, s37, 0
	global_load_lds_dwordx4 v[0:1], off
	s_add_i32 m0, s49, 0x1c000
	s_nop 0
	global_load_lds_dwordx4 v146, s[6:7]
	v_lshl_add_u64 v[0:1], s[6:7], 0, v[150:151]
	s_add_i32 m0, s49, 0x1e000
	v_and_b32_e32 v176, 15, v8
	global_load_lds_dwordx4 v[0:1], off
	s_waitcnt vmcnt(8)
	s_barrier
	v_bfe_u32 v1, v8, 4, 2
	v_or_b32_e32 v2, s3, v176
	s_sext_i32_i8 s31, s4
	v_lshlrev_b32_e32 v3, 6, v2
	v_lshlrev_b32_e32 v4, 4, v1
	s_movk_i32 s4, 0x3c0
	v_lshlrev_b32_e32 v2, 2, v2
	v_lshrrev_b32_e32 v0, 4, v8
	v_and_or_b32 v3, v3, s4, v4
	v_and_b32_e32 v2, 32, v2
	v_lshlrev_b32_e32 v5, 2, v8
	v_bitop3_b32 v2, v3, s42, v2 bitop3:0xde
	v_lshl_or_b32 v3, v176, 6, v4
	v_and_b32_e32 v5, 32, v5
	s_cmpk_lt_u32 s80, 0x100
	v_bfe_u32 v0, v0, 1, 1
	v_bitop3_b32 v177, v3, s41, v5 bitop3:0xde
	s_cselect_b64 s[18:19], -1, 0
	s_lshl_b32 s20, s33, 6
	v_lshl_or_b32 v0, s33, 1, v0
	v_and_or_b32 v3, v4, 16, v176
	v_readlane_b32 s6, v255, 1
	v_lshlrev_b32_e32 v152, 4, v3
	v_mul_u32_u24_e32 v3, 0x210, v0
	v_lshlrev_b32_e32 v154, 11, v0
	v_cmp_eq_u32_e64 s[4:5], 0, v1
	v_readlane_b32 s7, v255, 2
	s_ashr_i32 s56, s6, 31
	v_or_b32_e32 v0, s20, v4
	v_mov_b32_e32 v1, v147
	v_lshlrev_b32_e32 v5, 14, v9
	s_mov_b32 s57, s6
	v_lshl_add_u64 v[158:159], s[92:93], 0, v[0:1]
	s_mov_b64 s[6:7], 0x3400000
	s_add_u32 s58, s92, 0xb400000
	v_and_b32_e32 v5, 0xffff8000, v5
	v_lshl_add_u64 v[160:161], v[158:159], 0, s[6:7]
	s_addc_u32 s59, s93, 0
	s_add_i32 s6, s40, 0
	v_lshl_add_u32 v5, v10, 11, v5
	v_and_b32_e32 v6, 1, v9
	s_add_i32 s6, s6, 0x20000
	v_lshl_or_b32 v5, v6, 6, v5
	s_add_i32 s7, s20, s6
	v_lshl_add_u32 v162, v11, 1, v5
	v_lshlrev_b32_e32 v5, 14, v12
	s_movk_i32 s21, 0x210
	v_mov_b32_e32 v0, s7
	v_and_b32_e32 v5, 0xffff8000, v5
	s_waitcnt vmcnt(6)
	v_mad_u32_u24 v0, v176, s21, v0
	s_add_u32 s20, s92, 0x1f440000
	v_lshl_add_u32 v5, v13, 11, v5
	v_and_b32_e32 v6, 1, v12
	v_add_u32_e32 v1, s6, v152
	s_addc_u32 s21, s93, 0
	v_lshl_or_b32 v5, v6, 6, v5
	s_add_i32 s60, 0, 0x10000
	s_add_i32 s61, 0, 0x14000
	v_add_u32_e32 v181, v0, v4
	v_mbcnt_lo_u32_b32 v0, -1, 0
	v_mov_b32_e32 v153, v147
	v_mov_b32_e32 v155, v147
	v_or_b32_e32 v156, 0x4000, v154
	v_mov_b32_e32 v157, v147
	v_mov_b32_e32 v163, v147
	v_lshl_add_u32 v164, v14, 1, v5
	v_mov_b32_e32 v165, v147
	v_mov_b64_e32 v[166:167], 0x200
	v_mov_b64_e32 v[168:169], 0x1ff
	v_add_u32_e32 v178, s60, v177
	v_add_u32_e32 v179, s61, v177
	v_add_u32_e32 v180, 0, v2
	s_mov_b32 s62, 0x3400000
	v_add_u32_e32 v182, v1, v3
	v_mbcnt_hi_u32_b32 v183, -1, v0
	s_barrier
	s_branch .LBB0_1244

; #define PG8_STAGE(bufoff, gbase, voff) do { _Pragma("unroll") for (int _i = 0; _i < 2; ++_i) \
;         __builtin_amdgcn_global_load_lds((const unsigned*)((const char*)(gbase) + (voff)[_i]), (LAS unsigned*)(lds + (bufoff) + ldsw + _i * 8192), 16, 0, 0); } while (0)
; #define PG8_WAIT_V(n) asm volatile("s_waitcnt vmcnt(" #n ")" ::: "memory")
; #define PG8_BAR __builtin_amdgcn_s_barrier()
; template <class Epi, class Sched>
; __device__ __forceinline__ void gemm_phase(LAS unsigned char* lds, const Gemm g, const Sched& S, const Epi& E, int wave_id) {
;     ...
;     PG8_STAGE(PG8_SB(0, 0), cB, voffB); PG8_STAGE(PG8_SB(0, 1), cB + hstepB, voffB); PG8_STAGE(PG8_SA(0, 0), cA, voffA); PG8_STAGE(PG8_SA(0, 1), cA + hstepA, voffA);
;     if (wr == 1) PG8_BAR;
;     PG8_WAIT_V(2); PG8_BAR;
;     PG8_STAGE(PG8_SB(1, 0), cB + kstep, voffB); PG8_STAGE(PG8_SA(1, 0), cA + kstep, voffA); PG8_STAGE(PG8_SB(1, 1), cB + hstepB + kstep, voffB);
;     PG8_WAIT_V(6); PG8_BAR;
.LBB0_1267:
	s_add_u32 s56, s92, 0x13400000
	s_mov_b64 s[12:13], 0x80
	s_addc_u32 s57, s93, 0
	s_add_i32 m0, s51, 0x18000
	v_lshl_add_u64 v[6:7], v[6:7], 0, s[12:13]
	global_load_lds_dwordx4 v[6:7], off
	v_lshl_add_u64 v[4:5], v[4:5], 0, s[12:13]
	s_add_i32 m0, s51, 0x1a000
	s_add_i32 s58, s51, 0x8000
	s_add_i32 s59, s51, 0xa000
	global_load_lds_dwordx4 v[4:5], off
	v_lshl_add_u64 v[0:1], v[0:1], 0, s[12:13]
	s_mov_b32 m0, s58
	s_add_u32 s14, s26, 0x10080
	global_load_lds_dwordx4 v[0:1], off
	v_lshl_add_u64 v[0:1], v[2:3], 0, s[12:13]
	s_mov_b32 m0, s59
	s_addc_u32 s15, s27, 0
	global_load_lds_dwordx4 v[0:1], off
	s_add_i32 m0, s51, 0x1c000
	s_nop 0
	global_load_lds_dwordx4 v130, s[14:15]
	v_lshl_add_u64 v[0:1], s[14:15], 0, v[134:135]
	s_add_i32 m0, s51, 0x1e000
	v_and_b32_e32 v2, 15, v8
	global_load_lds_dwordx4 v[0:1], off
	s_waitcnt vmcnt(8)
	s_barrier
	v_lshrrev_b32_e32 v0, 4, v8
	v_bfe_u32 v1, v8, 4, 2
	v_or_b32_e32 v3, s3, v2
	s_sext_i32_i8 s25, s4
	v_lshlrev_b32_e32 v1, 4, v1
	v_lshlrev_b32_e32 v4, 6, v3
	s_movk_i32 s4, 0x3c0
	v_lshlrev_b32_e32 v3, 2, v3
	s_cmpk_lt_u32 s80, 0x100
	v_bfe_u32 v0, v0, 1, 1
	v_readlane_b32 s16, v255, 1
	v_and_or_b32 v4, v4, s4, v1
	v_and_b32_e32 v3, 32, v3
	v_lshlrev_b32_e32 v5, 2, v8
	s_cselect_b64 s[14:15], -1, 0
	v_lshl_or_b32 v0, s33, 1, v0
	s_lshl_b32 s5, s33, 6
	s_ashr_i32 s33, s16, 31
	s_mov_b32 s60, s16
	s_add_i32 s16, s40, 0
	v_bitop3_b32 v3, v4, s42, v3 bitop3:0xde
	v_lshl_or_b32 v4, v2, 6, v1
	v_and_b32_e32 v5, 32, v5
	s_add_i32 s16, s16, 0x20000
	v_bitop3_b32 v146, v4, s41, v5 bitop3:0xde
	v_and_or_b32 v4, v1, 16, v2
	s_add_i32 s5, s5, s16
	s_waitcnt vmcnt(6)
	v_lshlrev_b32_e32 v136, 4, v4
	s_movk_i32 s4, 0x210
	v_mov_b32_e32 v5, s5
	v_mul_u32_u24_e32 v4, 0x210, v0
	v_mad_u32_u24 v2, v2, s4, v5
	v_add_u32_e32 v5, s16, v136
	v_lshlrev_b32_e32 v138, 11, v0
	s_add_i32 s61, 0, 0x10000
	s_add_i32 s62, 0, 0x14000
	v_mov_b32_e32 v137, v131
	v_mov_b32_e32 v139, v131
	v_or_b32_e32 v140, 0x4000, v138
	v_mov_b32_e32 v141, v131
	v_mov_b64_e32 v[142:143], 0x200
	v_mov_b64_e32 v[144:145], 0x1ff
	v_add_u32_e32 v147, s61, v146
	v_add_u32_e32 v148, s62, v146
	v_add_u32_e32 v149, 0, v3
	v_add_u32_e32 v150, v2, v1
	v_add_u32_e32 v151, v5, v4
	s_barrier
	v_readlane_b32 s17, v255, 2
	s_waitcnt vmcnt(0)
	s_branch .LBB0_1270

; #define PG8_STAGE(bufoff, gbase, voff) do { _Pragma("unroll") for (int _i = 0; _i < 2; ++_i) \
;         __builtin_amdgcn_global_load_lds((const unsigned*)((const char*)(gbase) + (voff)[_i]), (LAS unsigned*)(lds + (bufoff) + ldsw + _i * 8192), 16, 0, 0); } while (0)
; #define PG8_WAIT_V(n) asm volatile("s_waitcnt vmcnt(" #n ")" ::: "memory")
; #define PG8_BAR __builtin_amdgcn_s_barrier()
; template <class Epi, class Sched>
; __device__ __forceinline__ void gemm_phase(LAS unsigned char* lds, const Gemm g, const Sched& S, const Epi& E, int wave_id) {
;     ...
;     PG8_STAGE(PG8_SB(0, 0), cB, voffB); PG8_STAGE(PG8_SB(0, 1), cB + hstepB, voffB); PG8_STAGE(PG8_SA(0, 0), cA, voffA); PG8_STAGE(PG8_SA(0, 1), cA + hstepA, voffA);
;     if (wr == 1) PG8_BAR;
;     PG8_WAIT_V(2); PG8_BAR;
;     PG8_STAGE(PG8_SB(1, 0), cB + kstep, voffB); PG8_STAGE(PG8_SA(1, 0), cA + kstep, voffA); PG8_STAGE(PG8_SB(1, 1), cB + hstepB + kstep, voffB);
;     PG8_WAIT_V(6); PG8_BAR;
.LBB0_1372:
	s_mov_b64 s[22:23], 0x80
	s_bfe_u32 s18, s80, 0x20006
	s_add_i32 m0, s37, 0x18000
	v_lshl_add_u64 v[6:7], v[6:7], 0, s[22:23]
	s_lshl_b32 s5, s6, 13
	s_lshl_b32 s36, s18, 5
	s_lshl_b32 s7, s18, 12
	global_load_lds_dwordx4 v[6:7], off
	v_lshl_add_u64 v[4:5], v[4:5], 0, s[22:23]
	s_add_i32 m0, s37, 0x1a000
	s_add_i32 s55, s37, 0x8000
	s_add_i32 s56, s37, 0xa000
	global_load_lds_dwordx4 v[4:5], off
	v_lshl_add_u64 v[0:1], v[0:1], 0, s[22:23]
	s_mov_b32 m0, s55
	s_add_u32 s8, s46, 0x40080
	global_load_lds_dwordx4 v[0:1], off
	v_lshl_add_u64 v[0:1], v[2:3], 0, s[22:23]
	s_mov_b32 m0, s56
	s_addc_u32 s9, s47, 0
	global_load_lds_dwordx4 v[0:1], off
	s_add_i32 m0, s37, 0x1c000
	s_nop 0
	global_load_lds_dwordx4 v154, s[8:9]
	v_lshl_add_u64 v[0:1], s[8:9], 0, v[158:159]
	s_add_i32 m0, s37, 0x1e000
	v_bfe_u32 v2, v9, 4, 2
	global_load_lds_dwordx4 v[0:1], off
	s_waitcnt vmcnt(8)
	s_barrier
	v_and_b32_e32 v1, 15, v9
	s_cmpk_lt_u32 s80, 0x100
	v_readlane_b32 s8, v255, 1
	v_lshl_or_b32 v163, s6, 6, v1
	v_lshlrev_b32_e32 v3, 4, v2
	v_lshlrev_b32_e32 v4, 2, v9
	s_cselect_b64 s[24:25], -1, 0
	s_or_b32 s6, s18, s6
	s_ashr_i32 s57, s8, 31
	s_mov_b32 s58, s8
	s_lshl_b32 s8, s18, 7
	v_lshl_or_b32 v3, v1, 6, v3
	v_and_b32_e32 v4, 32, v4
	v_or3_b32 v1, s6, v1, v2
	v_readlane_b32 s9, v255, 2
	s_add_u32 s8, s68, s8
	v_bitop3_b32 v165, v3, s7, v4 bitop3:0xde
	v_cmp_eq_u32_e64 s[6:7], 0, v1
	s_addc_u32 s9, s69, 0
	v_lshlrev_b32_e32 v1, 14, v8
	s_add_u32 s26, s92, 0x1f440000
	v_and_b32_e32 v1, 0xffff8000, v1
	s_sext_i32_i8 s11, s4
	v_lshlrev_b32_e32 v0, 3, v2
	v_bitop3_b32 v5, v3, s5, v4 bitop3:0xde
	v_cmp_eq_u32_e64 s[4:5], 0, v2
	v_lshlrev_b32_e32 v160, 5, v2
	s_addc_u32 s27, s93, 0
	v_lshl_add_u32 v1, v10, 11, v1
	v_and_b32_e32 v2, 1, v8
	s_add_u32 s28, s92, 0x13400000
	v_lshl_or_b32 v1, v2, 6, v1
	s_addc_u32 s29, s93, 0
	v_lshl_add_u32 v168, v11, 1, v1
	v_lshlrev_b32_e32 v1, 14, v12
	s_add_u32 s30, s92, 0x1f480000
	v_and_b32_e32 v1, 0xffff8000, v1
	s_addc_u32 s31, s93, 0
	v_lshl_add_u32 v1, v13, 11, v1
	v_and_b32_e32 v2, 1, v12
	s_waitcnt vmcnt(6)
	s_add_u32 s59, s92, 0x1f604000
	v_lshl_or_b32 v1, v2, 6, v1
	v_or_b32_e32 v162, s36, v0
	s_addc_u32 s60, s93, 0
	v_lshl_add_u32 v170, v14, 1, v1
	s_add_i32 s61, 0, 0x10000
	s_add_i32 s62, 0, 0x14000
	v_mbcnt_lo_u32_b32 v1, -1, 0
	v_or_b32_e32 v164, 0x80, v162
	v_lshl_add_u64 v[166:167], s[8:9], 0, v[160:161]
	v_mov_b32_e32 v169, v161
	v_mov_b32_e32 v171, v161
	v_mov_b64_e32 v[172:173], 0x200
	v_mov_b64_e32 v[174:175], 0x1ff
	v_add_u32_e32 v200, s61, v165
	v_add_u32_e32 v201, s62, v165
	v_add_u32_e32 v202, 0, v5
	v_mbcnt_hi_u32_b32 v203, -1, v1
	v_mov_b32_e32 v204, 0x358637bd
	s_mov_b32 s34, 0x3a800000
	s_mov_b32 s63, 0x800000
	s_lshl_b32 s18, s36, 2
	v_lshlrev_b32_e32 v160, 2, v0
	s_mov_b32 s36, 0x358637bd
	s_mov_b32 s64, s19
	s_barrier
	s_branch .LBB0_1375
